# A3 selection-mask: bfe/bfi pairs software-pipelined with two alternating temps so each bfi no longer directly follows its bfe
# speedup vs baseline: 1.0011x; 1.0011x over previous
; #define LAS __attribute__((address_space(3)))
; #define MFMA32(a, b, c) __builtin_amdgcn_mfma_f32_32x32x16_bf16((a), (b), (c), 0, 0, 0)
;     ...
;         const int key0 = kt * KT + sub * 32 * NKB;
;         if ((MODE == 0 || key0 <= q0 + 31) && PV != 2) {
;             unsigned long long mw[NKB / 2];
;             if (MODE == 0) {
; #pragma unroll
;                 for (int w = 0; w < NKB / 2; ++w) mw[w] = MASK64[(rowbase + q0 + r) * 32 + (key0 >> 6) + w];
;             }
;             f32x16 sv[NKB];
; #pragma unroll
;             for (int kb2 = 0; kb2 < NKB; ++kb2)
; #pragma unroll
;                 for (int i = 0; i < 16; ++i) sv[kb2][i] = nm_run;
;             const LAS unsigned char* kb_ = lds + st * STAGE + koff + sub * 32 * NKB * KP;
; #pragma unroll
;             for (int kh = 0; kh < 2; ++kh) {
;                 bf16x8 kfr[2][NKB];
; #pragma unroll
;                 for (int k2 = 0; k2 < 2; ++k2)
; #pragma unroll
;                     for (int kb2 = 0; kb2 < NKB; ++kb2) kfr[k2][kb2] = *(const LAS bf16x8*)(kb_ + (32 * kb2 + r) * KP + (2 * kh + k2) * 32 + h * 16);
;                 if (NKB == 2) asm volatile("" : "+v"(kfr[0][0]), "+v"(kfr[0][1]), "+v"(kfr[1][0]), "+v"(kfr[1][1]));
;                 else asm volatile("" : "+v"(kfr[0][0]), "+v"(kfr[0][1]), "+v"(kfr[0][NKB - 2]), "+v"(kfr[0][NKB - 1]), "+v"(kfr[1][0]), "+v"(kfr[1][1]), "+v"(kfr[1][NKB - 2]), "+v"(kfr[1][NKB - 1]));
; #pragma unroll
;                 for (int k2 = 0; k2 < 2; ++k2)
; #pragma unroll
;                     for (int kb2 = 0; kb2 < NKB; ++kb2) sv[kb2] = MFMA32(kfr[k2][kb2], qf[2 * kh + k2], sv[kb2]);
;             }
;             if (MODE == 0) {
; #pragma unroll
;                 for (int kb2 = 0; kb2 < NKB; ++kb2) {
;                     const unsigned wsel = ((kb2 & 1) ? (unsigned)(mw[kb2 >> 1] >> 32) : (unsigned)mw[kb2 >> 1]) >> (4 * h);
; #pragma unroll
;                     for (int i = 0; i < 16; ++i) { const int cb = (i & 3) + 8 * (i >> 2); if (!((wsel >> cb) & 1u)) sv[kb2][i] = -1e30f; }
.LBB0_522:
	v_lshl_add_u64 v[34:35], s[0:1], 0, v[166:167]
	v_add_co_u32_e32 v34, vcc, 0x1d600000, v34
	s_and_b32 s7, s6, 1
	s_nop 0
	v_addc_co_u32_e32 v35, vcc, 0, v35, vcc
	global_load_dwordx4 v[132:135], v[34:35], off
	s_mul_i32 s9, s7, 0x8a00
	s_add_i32 s9, s9, 0
	v_add3_u32 v185, s9, v180, v182
	ds_read_b128 v[186:189], v185 offset:13856
	ds_read_b128 v[190:193], v185 offset:9248
	ds_read_b128 v[200:203], v185 offset:4640
	ds_read_b128 v[204:207], v185 offset:13824
	ds_read_b128 v[208:211], v185 offset:9216
	ds_read_b128 v[48:51], v185 offset:4608
	ds_read_b128 v[52:55], v185
	ds_read_b128 v[212:215], v185 offset:32
	v_mov_b32_e32 v33, v32
	v_mov_b32_e32 v34, v32
	v_mov_b32_e32 v35, v32
	v_mov_b32_e32 v36, v32
	v_mov_b32_e32 v37, v32
	v_mov_b32_e32 v38, v32
	v_mov_b32_e32 v39, v32
	v_mov_b32_e32 v40, v32
	v_mov_b32_e32 v41, v32
	v_mov_b32_e32 v42, v32
	v_mov_b32_e32 v43, v32
	v_mov_b32_e32 v44, v32
	v_mov_b32_e32 v45, v32
	v_mov_b32_e32 v46, v32
	v_mov_b32_e32 v47, v32
	s_waitcnt lgkmcnt(0)
	s_nop 0
	v_mfma_f32_32x32x16_bf16 v[82:97], v[52:55], v[100:103], v[32:47]
	v_mfma_f32_32x32x16_bf16 v[66:81], v[48:51], v[100:103], v[32:47]
	v_mfma_f32_32x32x16_bf16 v[50:65], v[208:211], v[100:103], v[32:47]
	v_mov_b64_e32 v[48:49], v[46:47]
	s_nop 5
	v_mov_b64_e32 v[46:47], v[44:45]
	v_mov_b64_e32 v[44:45], v[42:43]
	v_mov_b64_e32 v[42:43], v[40:41]
	v_mov_b64_e32 v[40:41], v[38:39]
	v_mov_b64_e32 v[38:39], v[36:37]
	v_mov_b64_e32 v[36:37], v[34:35]
	v_mov_b64_e32 v[34:35], v[32:33]
	v_mfma_f32_32x32x16_bf16 v[82:97], v[212:215], v[104:107], v[82:97]
	s_waitcnt vmcnt(0)
	v_lshrrev_b32_e32 v132, v150, v132
	v_lshrrev_b32_e32 v133, v150, v133
	v_lshrrev_b32_e32 v134, v150, v134
	v_lshrrev_b32_e32 v135, v150, v135
	v_mfma_f32_32x32x16_bf16 v[34:49], v[204:207], v[100:103], v[34:49]
	v_mfma_f32_32x32x16_bf16 v[66:81], v[200:203], v[104:107], v[66:81]
	v_mfma_f32_32x32x16_bf16 v[50:65], v[190:193], v[104:107], v[50:65]
	v_mfma_f32_32x32x16_bf16 v[34:49], v[186:189], v[104:107], v[34:49]
	ds_read_b128 v[186:189], v185 offset:13920
	ds_read_b128 v[190:193], v185 offset:9312
	ds_read_b128 v[200:203], v185 offset:4704
	ds_read_b128 v[204:207], v185 offset:13888
	ds_read_b128 v[208:211], v185 offset:9280
	ds_read_b128 v[212:215], v185 offset:4672
	ds_read_b128 v[216:219], v185 offset:64
	ds_read_b128 v[220:223], v185 offset:96
	s_waitcnt lgkmcnt(0)
	s_nop 0
	v_mfma_f32_32x32x16_bf16 v[82:97], v[216:219], v[108:111], v[82:97]
	v_mfma_f32_32x32x16_bf16 v[82:97], v[220:223], v[112:115], v[82:97]
	v_mfma_f32_32x32x16_bf16 v[66:81], v[212:215], v[108:111], v[66:81]
	s_nop 10
	v_bfe_i32 v224, v132, 0, 1
	v_bfe_i32 v225, v132, 1, 1
	v_bfi_b32 v82, v224, v82, v235
	v_bfe_i32 v224, v132, 2, 1
	v_mfma_f32_32x32x16_bf16 v[66:81], v[200:203], v[112:115], v[66:81]
	v_bfi_b32 v83, v225, v83, v235
	v_bfe_i32 v225, v132, 3, 1
	v_bfi_b32 v84, v224, v84, v235
	v_bfe_i32 v224, v132, 8, 1
	v_mfma_f32_32x32x16_bf16 v[50:65], v[208:211], v[108:111], v[50:65]
	v_bfi_b32 v85, v225, v85, v235
	v_bfe_i32 v225, v132, 9, 1
	v_bfi_b32 v86, v224, v86, v235
	v_bfe_i32 v224, v132, 10, 1
	v_mfma_f32_32x32x16_bf16 v[50:65], v[190:193], v[112:115], v[50:65]
	v_bfi_b32 v87, v225, v87, v235
	v_bfe_i32 v225, v132, 11, 1
	v_bfi_b32 v88, v224, v88, v235
	v_bfe_i32 v224, v132, 16, 1
	v_mfma_f32_32x32x16_bf16 v[34:49], v[204:207], v[108:111], v[34:49]
	v_bfi_b32 v89, v225, v89, v235
	v_bfe_i32 v225, v132, 17, 1
	v_bfi_b32 v90, v224, v90, v235
	v_bfe_i32 v224, v132, 18, 1
	v_mfma_f32_32x32x16_bf16 v[34:49], v[186:189], v[112:115], v[34:49]
	v_bfi_b32 v91, v225, v91, v235
	v_bfe_i32 v225, v132, 19, 1
	v_bfi_b32 v92, v224, v92, v235
	v_bfe_i32 v224, v132, 24, 1
	v_bfi_b32 v93, v225, v93, v235
	v_bfe_i32 v225, v132, 25, 1
	v_bfi_b32 v94, v224, v94, v235
	v_bfe_i32 v224, v132, 26, 1
	v_bfi_b32 v95, v225, v95, v235
	v_bfe_i32 v225, v132, 27, 1
	v_bfi_b32 v96, v224, v96, v235
	v_bfe_i32 v224, v133, 0, 1
	v_bfi_b32 v97, v225, v97, v235
	v_bfe_i32 v225, v133, 1, 1
	v_bfi_b32 v66, v224, v66, v235
	v_bfe_i32 v224, v133, 2, 1
	v_bfi_b32 v67, v225, v67, v235
	v_bfe_i32 v225, v133, 3, 1
	v_bfi_b32 v68, v224, v68, v235
	v_bfe_i32 v224, v133, 8, 1
	v_bfi_b32 v69, v225, v69, v235
	v_bfe_i32 v225, v133, 9, 1
	v_bfi_b32 v70, v224, v70, v235
	v_bfe_i32 v224, v133, 10, 1
	v_bfi_b32 v71, v225, v71, v235
	v_bfe_i32 v225, v133, 11, 1
	v_bfi_b32 v72, v224, v72, v235
	v_bfe_i32 v224, v133, 16, 1
	v_bfi_b32 v73, v225, v73, v235
	v_bfe_i32 v225, v133, 17, 1
	v_bfi_b32 v74, v224, v74, v235
	v_bfe_i32 v224, v133, 18, 1
	v_bfi_b32 v75, v225, v75, v235
	v_bfe_i32 v225, v133, 19, 1
	v_bfi_b32 v76, v224, v76, v235
	v_bfe_i32 v224, v133, 24, 1
	v_bfi_b32 v77, v225, v77, v235
	v_bfe_i32 v225, v133, 25, 1
	v_bfi_b32 v78, v224, v78, v235
	v_bfe_i32 v224, v133, 26, 1
	v_bfi_b32 v79, v225, v79, v235
	v_bfe_i32 v225, v133, 27, 1
	v_bfi_b32 v80, v224, v80, v235
	v_bfe_i32 v224, v134, 0, 1
	v_bfi_b32 v81, v225, v81, v235
	v_bfe_i32 v225, v134, 1, 1
	v_bfi_b32 v50, v224, v50, v235
	v_bfe_i32 v224, v134, 2, 1
	v_bfi_b32 v51, v225, v51, v235
	v_bfe_i32 v225, v134, 3, 1
	v_bfi_b32 v52, v224, v52, v235
	v_bfe_i32 v224, v134, 8, 1
	v_bfi_b32 v53, v225, v53, v235
	v_bfe_i32 v225, v134, 9, 1
	v_bfi_b32 v54, v224, v54, v235
	v_bfe_i32 v224, v134, 10, 1
	v_bfi_b32 v55, v225, v55, v235
	v_bfe_i32 v225, v134, 11, 1
	v_bfi_b32 v56, v224, v56, v235
	v_bfe_i32 v224, v134, 16, 1
	v_bfi_b32 v57, v225, v57, v235
	v_bfe_i32 v225, v134, 17, 1
	v_bfi_b32 v58, v224, v58, v235
	v_bfe_i32 v224, v134, 18, 1
	v_bfi_b32 v59, v225, v59, v235
	v_bfe_i32 v225, v134, 19, 1
	v_bfi_b32 v60, v224, v60, v235
	v_bfe_i32 v224, v134, 24, 1
	v_bfi_b32 v61, v225, v61, v235
; DI float shx(float v, int o, int lane) { return __int_as_float(__builtin_amdgcn_ds_bpermute((lane ^ o) << 2, __float_as_int(v))); }
; DI int crow(int i, int h) { return (i & 3) + 8 * (i >> 2) + 4 * h; }
;     ...
;                     for (int i = 0; i < 16; ++i) { const int cb = (i & 3) + 8 * (i >> 2); if (!((wsel >> cb) & 1u)) sv[kb2][i] = -1e30f; }
;                 }
;             } else if (key0 + 32 * NKB - 1 > q0) {
;                 const int qq = q0 + r;
; #pragma unroll
;                 for (int kb2 = 0; kb2 < NKB; ++kb2)
; #pragma unroll
;                     for (int i = 0; i < 16; ++i) { if (key0 + 32 * kb2 + crow(i, h) > qq) sv[kb2][i] = -1e30f; }
;             }
;             float mx = -1e30f;
; #pragma unroll
;             for (int kb2 = 0; kb2 < NKB; ++kb2)
; #pragma unroll
;                 for (int i = 0; i < 16; ++i) mx = __builtin_fmaxf(mx, sv[kb2][i]);
;             mx = __builtin_fmaxf(mx, shx(mx, 32, lane));
;             if (__ballot(mx > 8.0f)) {
;                 const float delta = __builtin_fmaxf(mx, 0.f);
;                 const float alpha = __builtin_amdgcn_exp2f(-delta);
;                 nm_run -= delta; l_run *= alpha;
; #pragma unroll
;                 for (int kb2 = 0; kb2 < NKB; ++kb2)
; #pragma unroll
;                     for (int i = 0; i < 16; ++i) sv[kb2][i] -= delta;
; #pragma unroll
;                 for (int db = 0; db < NDB; ++db)
; #pragma unroll
;                     for (int i = 0; i < 16; ++i) ot[db][i] *= alpha;
	v_bfe_i32 v225, v134, 25, 1
	v_bfi_b32 v62, v224, v62, v235
	v_bfe_i32 v224, v134, 26, 1
	v_bfi_b32 v63, v225, v63, v235
	v_bfe_i32 v225, v134, 27, 1
	v_bfi_b32 v64, v224, v64, v235
	v_bfe_i32 v224, v135, 0, 1
	v_bfi_b32 v65, v225, v65, v235
	v_bfe_i32 v225, v135, 1, 1
	v_bfi_b32 v34, v224, v34, v235
	v_bfe_i32 v224, v135, 2, 1
	v_bfi_b32 v35, v225, v35, v235
	v_bfe_i32 v225, v135, 3, 1
	v_bfi_b32 v36, v224, v36, v235
	v_bfe_i32 v224, v135, 8, 1
	v_bfi_b32 v37, v225, v37, v235
	v_bfe_i32 v225, v135, 9, 1
	v_bfi_b32 v38, v224, v38, v235
	v_bfe_i32 v224, v135, 10, 1
	v_bfi_b32 v39, v225, v39, v235
	v_bfe_i32 v225, v135, 11, 1
	v_bfi_b32 v40, v224, v40, v235
	v_bfe_i32 v224, v135, 16, 1
	v_bfi_b32 v41, v225, v41, v235
	v_bfe_i32 v225, v135, 17, 1
	v_bfi_b32 v42, v224, v42, v235
	v_bfe_i32 v224, v135, 18, 1
	v_bfi_b32 v43, v225, v43, v235
	v_bfe_i32 v225, v135, 19, 1
	v_bfi_b32 v44, v224, v44, v235
	v_bfe_i32 v224, v135, 24, 1
	v_bfi_b32 v45, v225, v45, v235
	v_bfe_i32 v225, v135, 25, 1
	v_bfi_b32 v46, v224, v46, v235
	v_bfe_i32 v224, v135, 26, 1
	v_bfi_b32 v47, v225, v47, v235
	v_bfe_i32 v225, v135, 27, 1
	v_max3_f32 v33, v82, s61, v83
	v_max3_f32 v33, v33, v84, v85
	v_max3_f32 v33, v33, v86, v87
	v_max3_f32 v33, v33, v88, v89
	v_max3_f32 v33, v33, v90, v91
	v_max3_f32 v33, v33, v92, v93
	v_max3_f32 v33, v33, v94, v95
	v_max3_f32 v33, v33, v96, v97
	v_max3_f32 v33, v33, v66, v67
	v_max3_f32 v33, v33, v68, v69
	v_max3_f32 v33, v33, v70, v71
	v_max3_f32 v33, v33, v72, v73
	v_max3_f32 v33, v33, v74, v75
	v_max3_f32 v33, v33, v76, v77
	v_max3_f32 v33, v33, v78, v79
	v_max3_f32 v33, v33, v80, v81
	v_max3_f32 v33, v33, v50, v51
	v_max3_f32 v33, v33, v52, v53
	v_max3_f32 v33, v33, v54, v55
	v_max3_f32 v33, v33, v56, v57
	v_max3_f32 v33, v33, v58, v59
	v_max3_f32 v33, v33, v60, v61
	v_max3_f32 v33, v33, v62, v63
	v_max3_f32 v33, v33, v64, v65
	v_max3_f32 v33, v33, v34, v35
	v_max3_f32 v33, v33, v36, v37
	v_max3_f32 v33, v33, v38, v39
	v_max3_f32 v33, v33, v40, v41
	v_max3_f32 v33, v33, v42, v43
	v_max3_f32 v33, v33, v44, v45
	v_bfi_b32 v48, v224, v48, v235
	v_bfi_b32 v49, v225, v49, v235
	v_max3_f32 v33, v33, v46, v47
	v_max3_f32 v33, v33, v48, v49
	ds_bpermute_b32 v132, v181, v33
	s_waitcnt lgkmcnt(0)
	v_max_f32_e32 v132, v132, v132
	v_max_f32_e32 v33, v33, v132
	v_cmp_lt_f32_e32 vcc, s33, v33
	s_cbranch_vccz .LBB0_524
	v_max_f32_e32 v33, v33, v33
	v_max_f32_e32 v132, 0, v33
	v_exp_f32_e64 v134, -v132
	v_sub_f32_e32 v32, v32, v132
	v_pk_add_f32 v[82:83], v[82:83], v[132:133] op_sel_hi:[1,0] neg_lo:[0,1] neg_hi:[0,1]
	v_pk_add_f32 v[84:85], v[84:85], v[132:133] op_sel_hi:[1,0] neg_lo:[0,1] neg_hi:[0,1]
	v_pk_add_f32 v[86:87], v[86:87], v[132:133] op_sel_hi:[1,0] neg_lo:[0,1] neg_hi:[0,1]
	v_pk_add_f32 v[88:89], v[88:89], v[132:133] op_sel_hi:[1,0] neg_lo:[0,1] neg_hi:[0,1]
	v_pk_add_f32 v[90:91], v[90:91], v[132:133] op_sel_hi:[1,0] neg_lo:[0,1] neg_hi:[0,1]
	v_pk_add_f32 v[92:93], v[92:93], v[132:133] op_sel_hi:[1,0] neg_lo:[0,1] neg_hi:[0,1]
	v_pk_add_f32 v[94:95], v[94:95], v[132:133] op_sel_hi:[1,0] neg_lo:[0,1] neg_hi:[0,1]
	v_pk_add_f32 v[96:97], v[96:97], v[132:133] op_sel_hi:[1,0] neg_lo:[0,1] neg_hi:[0,1]
	v_pk_add_f32 v[66:67], v[66:67], v[132:133] op_sel_hi:[1,0] neg_lo:[0,1] neg_hi:[0,1]
	v_pk_add_f32 v[68:69], v[68:69], v[132:133] op_sel_hi:[1,0] neg_lo:[0,1] neg_hi:[0,1]
	v_pk_add_f32 v[70:71], v[70:71], v[132:133] op_sel_hi:[1,0] neg_lo:[0,1] neg_hi:[0,1]
	v_pk_add_f32 v[72:73], v[72:73], v[132:133] op_sel_hi:[1,0] neg_lo:[0,1] neg_hi:[0,1]
	v_pk_add_f32 v[74:75], v[74:75], v[132:133] op_sel_hi:[1,0] neg_lo:[0,1] neg_hi:[0,1]
	v_pk_add_f32 v[76:77], v[76:77], v[132:133] op_sel_hi:[1,0] neg_lo:[0,1] neg_hi:[0,1]
	v_pk_add_f32 v[78:79], v[78:79], v[132:133] op_sel_hi:[1,0] neg_lo:[0,1] neg_hi:[0,1]
	v_pk_add_f32 v[80:81], v[80:81], v[132:133] op_sel_hi:[1,0] neg_lo:[0,1] neg_hi:[0,1]
	v_pk_add_f32 v[50:51], v[50:51], v[132:133] op_sel_hi:[1,0] neg_lo:[0,1] neg_hi:[0,1]
	v_pk_add_f32 v[52:53], v[52:53], v[132:133] op_sel_hi:[1,0] neg_lo:[0,1] neg_hi:[0,1]
	v_pk_add_f32 v[54:55], v[54:55], v[132:133] op_sel_hi:[1,0] neg_lo:[0,1] neg_hi:[0,1]
	v_pk_add_f32 v[56:57], v[56:57], v[132:133] op_sel_hi:[1,0] neg_lo:[0,1] neg_hi:[0,1]
	v_pk_add_f32 v[58:59], v[58:59], v[132:133] op_sel_hi:[1,0] neg_lo:[0,1] neg_hi:[0,1]
	v_pk_add_f32 v[60:61], v[60:61], v[132:133] op_sel_hi:[1,0] neg_lo:[0,1] neg_hi:[0,1]
	v_pk_add_f32 v[62:63], v[62:63], v[132:133] op_sel_hi:[1,0] neg_lo:[0,1] neg_hi:[0,1]
	v_pk_add_f32 v[64:65], v[64:65], v[132:133] op_sel_hi:[1,0] neg_lo:[0,1] neg_hi:[0,1]
	v_pk_add_f32 v[34:35], v[34:35], v[132:133] op_sel_hi:[1,0] neg_lo:[0,1] neg_hi:[0,1]
	v_pk_add_f32 v[36:37], v[36:37], v[132:133] op_sel_hi:[1,0] neg_lo:[0,1] neg_hi:[0,1]
	v_pk_add_f32 v[38:39], v[38:39], v[132:133] op_sel_hi:[1,0] neg_lo:[0,1] neg_hi:[0,1]
	v_pk_add_f32 v[40:41], v[40:41], v[132:133] op_sel_hi:[1,0] neg_lo:[0,1] neg_hi:[0,1]
	v_pk_add_f32 v[42:43], v[42:43], v[132:133] op_sel_hi:[1,0] neg_lo:[0,1] neg_hi:[0,1]
	v_pk_add_f32 v[44:45], v[44:45], v[132:133] op_sel_hi:[1,0] neg_lo:[0,1] neg_hi:[0,1]
	v_pk_add_f32 v[46:47], v[46:47], v[132:133] op_sel_hi:[1,0] neg_lo:[0,1] neg_hi:[0,1]
	v_pk_add_f32 v[48:49], v[48:49], v[132:133] op_sel_hi:[1,0] neg_lo:[0,1] neg_hi:[0,1]
	v_pk_mul_f32 v[14:15], v[14:15], v[134:135] op_sel_hi:[1,0]
	v_pk_mul_f32 v[12:13], v[12:13], v[134:135] op_sel_hi:[1,0]
	v_pk_mul_f32 v[10:11], v[10:11], v[134:135] op_sel_hi:[1,0]
	v_pk_mul_f32 v[8:9], v[8:9], v[134:135] op_sel_hi:[1,0]
	v_pk_mul_f32 v[6:7], v[6:7], v[134:135] op_sel_hi:[1,0]
	v_pk_mul_f32 v[4:5], v[4:5], v[134:135] op_sel_hi:[1,0]
	v_pk_mul_f32 v[2:3], v[2:3], v[134:135] op_sel_hi:[1,0]
	v_pk_mul_f32 v[0:1], v[0:1], v[134:135] op_sel_hi:[1,0]
	v_pk_mul_f32 v[30:31], v[30:31], v[134:135] op_sel_hi:[1,0]
	v_pk_mul_f32 v[28:29], v[28:29], v[134:135] op_sel_hi:[1,0]
	v_pk_mul_f32 v[26:27], v[26:27], v[134:135] op_sel_hi:[1,0]
	v_pk_mul_f32 v[24:25], v[24:25], v[134:135] op_sel_hi:[1,0]
	v_pk_mul_f32 v[22:23], v[22:23], v[134:135] op_sel_hi:[1,0]
	v_pk_mul_f32 v[20:21], v[20:21], v[134:135] op_sel_hi:[1,0]
	v_pk_mul_f32 v[18:19], v[18:19], v[134:135] op_sel_hi:[1,0]
	v_pk_mul_f32 v[16:17], v[16:17], v[134:135] op_sel_hi:[1,0]
	v_mul_f32_e32 v184, v184, v134
